# combo: P0 rows loop 2-deep prefetch + cvt_pk packs in P0 + per-token vmcnt waits in streaming K pass
# speedup vs baseline: 1.0073x; 1.0073x over previous
.Lpost_getpc1:
	s_add_u32 s98, s98, (.LBB0_930-.Lpost_getpc1)&4294967295
	s_addc_u32 s99, s99, (.LBB0_930-.Lpost_getpc1)>>32
	s_setpc_b64 s[98:99]
	s_nop 0
	s_nop 0
	s_nop 0
	s_nop 0
	s_nop 0
	s_nop 0
	s_nop 0
	s_nop 0
	s_nop 0
	s_nop 0
	s_nop 0
	s_nop 0
	s_nop 0
	s_nop 0
	s_nop 0
	s_nop 0
	s_nop 0
	s_nop 0
	s_nop 0
	s_nop 0
	s_nop 0
	s_nop 0
	s_nop 0
	s_nop 0
	s_nop 0
	s_nop 0
	s_nop 0
	s_nop 0
	s_nop 0
	s_nop 0
	s_nop 0
	s_nop 0
	s_nop 0
	s_nop 0
	s_nop 0
	s_nop 0
	s_nop 0
	s_nop 0
	s_nop 0
	s_nop 0
	s_nop 0
	s_nop 0
	s_nop 0
	s_nop 0
	s_nop 0
	s_nop 0
	s_nop 0
	s_nop 0
	s_nop 0
	s_nop 0
	s_nop 0
	s_nop 0
	s_nop 0
	s_nop 0
	s_nop 0
	s_nop 0
	s_nop 0
	s_nop 0
